# ev_in/odin bf16 store paths: all four 32x32 blocks staged through the LDS strip back to back (one lgkmcnt wait per tile instead of four), then the 8 dwordx4 stores
# speedup vs baseline: 1.0077x; 1.0046x over previous
.Levin1_notr:
	s_cmp_eq_u32 s24, 2
	s_cbranch_scc1 .LBB0_259
	s_cmp_eq_u32 s24, 7
	s_cbranch_scc1 .LBB0_259
	s_cmp_ge_u32 s24, 3
	s_cselect_b32 s2, 1, 0
	s_sub_u32 s2, s24, s2
	s_cmp_ge_u32 s24, 8
	s_cselect_b32 s3, 1, 0
	s_sub_u32 s2, s2, s3
	s_lshl_b32 s2, s2, 9
	s_add_u32 s2, s2, s0
	s_lshl_b32 s2, s2, 1
	s_mul_i32 s3, s1, 0x1c00
	s_add_u32 s2, s2, s3
	s_add_u32 s98, s90, 0x3971900
	s_addc_u32 s99, s91, 0
	s_add_u32 s98, s98, s2
	s_addc_u32 s99, s99, 0
	v_cvt_pk_bf16_f32 v64, v48, v49
	v_cvt_pk_bf16_f32 v65, v50, v51
	v_cvt_pk_bf16_f32 v66, v52, v53
	v_cvt_pk_bf16_f32 v67, v54, v55
	v_cvt_pk_bf16_f32 v68, v56, v57
	v_cvt_pk_bf16_f32 v69, v58, v59
	v_cvt_pk_bf16_f32 v70, v60, v61
	v_cvt_pk_bf16_f32 v71, v62, v63
	ds_write_b16 v112, v64
	ds_write_b16_d16_hi v112, v64 offset:64
	ds_write_b16 v112, v65 offset:128
	ds_write_b16_d16_hi v112, v65 offset:192
	ds_write_b16 v112, v66 offset:512
	ds_write_b16_d16_hi v112, v66 offset:576
	ds_write_b16 v112, v67 offset:640
	ds_write_b16_d16_hi v112, v67 offset:704
	ds_write_b16 v112, v68 offset:1024
	ds_write_b16_d16_hi v112, v68 offset:1088
	ds_write_b16 v112, v69 offset:1152
	ds_write_b16_d16_hi v112, v69 offset:1216
	ds_write_b16 v112, v70 offset:1536
	ds_write_b16_d16_hi v112, v70 offset:1600
	ds_write_b16 v112, v71 offset:1664
	ds_write_b16_d16_hi v112, v71 offset:1728
	ds_read_b128 v[80:83], v113
	ds_read_b128 v[84:87], v113 offset:1024
	v_cvt_pk_bf16_f32 v72, v16, v17
	v_cvt_pk_bf16_f32 v73, v18, v19
	v_cvt_pk_bf16_f32 v74, v20, v21
	v_cvt_pk_bf16_f32 v75, v22, v23
	v_cvt_pk_bf16_f32 v76, v24, v25
	v_cvt_pk_bf16_f32 v77, v26, v27
	v_cvt_pk_bf16_f32 v78, v28, v29
	v_cvt_pk_bf16_f32 v79, v30, v31
	ds_write_b16 v112, v72
	ds_write_b16_d16_hi v112, v72 offset:64
	ds_write_b16 v112, v73 offset:128
	ds_write_b16_d16_hi v112, v73 offset:192
	ds_write_b16 v112, v74 offset:512
	ds_write_b16_d16_hi v112, v74 offset:576
	ds_write_b16 v112, v75 offset:640
	ds_write_b16_d16_hi v112, v75 offset:704
	ds_write_b16 v112, v76 offset:1024
	ds_write_b16_d16_hi v112, v76 offset:1088
	ds_write_b16 v112, v77 offset:1152
	ds_write_b16_d16_hi v112, v77 offset:1216
	ds_write_b16 v112, v78 offset:1536
	ds_write_b16_d16_hi v112, v78 offset:1600
	ds_write_b16 v112, v79 offset:1664
	ds_write_b16_d16_hi v112, v79 offset:1728
	ds_read_b128 v[88:91], v113
	ds_read_b128 v[92:95], v113 offset:1024
	v_cvt_pk_bf16_f32 v64, v32, v33
	v_cvt_pk_bf16_f32 v65, v34, v35
	v_cvt_pk_bf16_f32 v66, v36, v37
	v_cvt_pk_bf16_f32 v67, v38, v39
	v_cvt_pk_bf16_f32 v68, v40, v41
	v_cvt_pk_bf16_f32 v69, v42, v43
	v_cvt_pk_bf16_f32 v70, v44, v45
	v_cvt_pk_bf16_f32 v71, v46, v47
	ds_write_b16 v112, v64
	ds_write_b16_d16_hi v112, v64 offset:64
	ds_write_b16 v112, v65 offset:128
	ds_write_b16_d16_hi v112, v65 offset:192
	ds_write_b16 v112, v66 offset:512
	ds_write_b16_d16_hi v112, v66 offset:576
	ds_write_b16 v112, v67 offset:640
	ds_write_b16_d16_hi v112, v67 offset:704
	ds_write_b16 v112, v68 offset:1024
	ds_write_b16_d16_hi v112, v68 offset:1088
	ds_write_b16 v112, v69 offset:1152
	ds_write_b16_d16_hi v112, v69 offset:1216
	ds_write_b16 v112, v70 offset:1536
	ds_write_b16_d16_hi v112, v70 offset:1600
	ds_write_b16 v112, v71 offset:1664
	ds_write_b16_d16_hi v112, v71 offset:1728
	ds_read_b128 v[96:99], v113
	ds_read_b128 v[100:103], v113 offset:1024
	v_cvt_pk_bf16_f32 v72, v0, v1
	v_cvt_pk_bf16_f32 v73, v2, v3
	v_cvt_pk_bf16_f32 v74, v4, v5
	v_cvt_pk_bf16_f32 v75, v6, v7
	v_cvt_pk_bf16_f32 v76, v8, v9
	v_cvt_pk_bf16_f32 v77, v10, v11
	v_cvt_pk_bf16_f32 v78, v12, v13
	v_cvt_pk_bf16_f32 v79, v14, v15
	ds_write_b16 v112, v72
	ds_write_b16_d16_hi v112, v72 offset:64
	ds_write_b16 v112, v73 offset:128
	ds_write_b16_d16_hi v112, v73 offset:192
	ds_write_b16 v112, v74 offset:512
	ds_write_b16_d16_hi v112, v74 offset:576
	ds_write_b16 v112, v75 offset:640
	ds_write_b16_d16_hi v112, v75 offset:704
	ds_write_b16 v112, v76 offset:1024
	ds_write_b16_d16_hi v112, v76 offset:1088
	ds_write_b16 v112, v77 offset:1152
	ds_write_b16_d16_hi v112, v77 offset:1216
	ds_write_b16 v112, v78 offset:1536
	ds_write_b16_d16_hi v112, v78 offset:1600
	ds_write_b16 v112, v79 offset:1664
	ds_write_b16_d16_hi v112, v79 offset:1728
	ds_read_b128 v[104:107], v113
	ds_read_b128 v[108:111], v113 offset:1024
	s_waitcnt lgkmcnt(0)
	global_store_dwordx4 v114, v[80:83], s[98:99]
	s_add_u32 s100, s98, 0x1c000
	s_addc_u32 s101, s99, 0
	global_store_dwordx4 v114, v[84:87], s[100:101]
	global_store_dwordx4 v114, v[88:91], s[98:99] offset:64
	global_store_dwordx4 v114, v[92:95], s[100:101] offset:64
	s_add_u32 s98, s98, 0x38000
	s_addc_u32 s99, s99, 0
	global_store_dwordx4 v114, v[96:99], s[98:99]
	s_add_u32 s100, s98, 0x1c000
	s_addc_u32 s101, s99, 0
	global_store_dwordx4 v114, v[100:103], s[100:101]
	global_store_dwordx4 v114, v[104:107], s[98:99] offset:64
	global_store_dwordx4 v114, v[108:111], s[100:101] offset:64
	s_branch .LBB0_259

.Lodin4_nat:
	s_lshl_b32 s8, s7, 11
	s_add_u32 s8, s8, s9
	s_lshl_b32 s9, s6, 1
	s_add_u32 s8, s8, s9
	s_add_u32 s98, s90, s8
	s_addc_u32 s99, s91, 0
	v_cvt_pk_bf16_f32 v64, v48, v49
	v_cvt_pk_bf16_f32 v65, v50, v51
	v_cvt_pk_bf16_f32 v66, v52, v53
	v_cvt_pk_bf16_f32 v67, v54, v55
	v_cvt_pk_bf16_f32 v68, v56, v57
	v_cvt_pk_bf16_f32 v69, v58, v59
	v_cvt_pk_bf16_f32 v70, v60, v61
	v_cvt_pk_bf16_f32 v71, v62, v63
	ds_write_b16 v112, v64
	ds_write_b16_d16_hi v112, v64 offset:64
	ds_write_b16 v112, v65 offset:128
	ds_write_b16_d16_hi v112, v65 offset:192
	ds_write_b16 v112, v66 offset:512
	ds_write_b16_d16_hi v112, v66 offset:576
	ds_write_b16 v112, v67 offset:640
	ds_write_b16_d16_hi v112, v67 offset:704
	ds_write_b16 v112, v68 offset:1024
	ds_write_b16_d16_hi v112, v68 offset:1088
	ds_write_b16 v112, v69 offset:1152
	ds_write_b16_d16_hi v112, v69 offset:1216
	ds_write_b16 v112, v70 offset:1536
	ds_write_b16_d16_hi v112, v70 offset:1600
	ds_write_b16 v112, v71 offset:1664
	ds_write_b16_d16_hi v112, v71 offset:1728
	ds_read_b128 v[80:83], v113
	ds_read_b128 v[84:87], v113 offset:1024
	v_cvt_pk_bf16_f32 v72, v16, v17
	v_cvt_pk_bf16_f32 v73, v18, v19
	v_cvt_pk_bf16_f32 v74, v20, v21
	v_cvt_pk_bf16_f32 v75, v22, v23
	v_cvt_pk_bf16_f32 v76, v24, v25
	v_cvt_pk_bf16_f32 v77, v26, v27
	v_cvt_pk_bf16_f32 v78, v28, v29
	v_cvt_pk_bf16_f32 v79, v30, v31
	ds_write_b16 v112, v72
	ds_write_b16_d16_hi v112, v72 offset:64
	ds_write_b16 v112, v73 offset:128
	ds_write_b16_d16_hi v112, v73 offset:192
	ds_write_b16 v112, v74 offset:512
	ds_write_b16_d16_hi v112, v74 offset:576
	ds_write_b16 v112, v75 offset:640
	ds_write_b16_d16_hi v112, v75 offset:704
	ds_write_b16 v112, v76 offset:1024
	ds_write_b16_d16_hi v112, v76 offset:1088
	ds_write_b16 v112, v77 offset:1152
	ds_write_b16_d16_hi v112, v77 offset:1216
	ds_write_b16 v112, v78 offset:1536
	ds_write_b16_d16_hi v112, v78 offset:1600
	ds_write_b16 v112, v79 offset:1664
	ds_write_b16_d16_hi v112, v79 offset:1728
	ds_read_b128 v[88:91], v113
	ds_read_b128 v[92:95], v113 offset:1024
	v_cvt_pk_bf16_f32 v64, v32, v33
	v_cvt_pk_bf16_f32 v65, v34, v35
	v_cvt_pk_bf16_f32 v66, v36, v37
	v_cvt_pk_bf16_f32 v67, v38, v39
	v_cvt_pk_bf16_f32 v68, v40, v41
	v_cvt_pk_bf16_f32 v69, v42, v43
	v_cvt_pk_bf16_f32 v70, v44, v45
	v_cvt_pk_bf16_f32 v71, v46, v47
	ds_write_b16 v112, v64
	ds_write_b16_d16_hi v112, v64 offset:64
	ds_write_b16 v112, v65 offset:128
	ds_write_b16_d16_hi v112, v65 offset:192
	ds_write_b16 v112, v66 offset:512
	ds_write_b16_d16_hi v112, v66 offset:576
	ds_write_b16 v112, v67 offset:640
	ds_write_b16_d16_hi v112, v67 offset:704
	ds_write_b16 v112, v68 offset:1024
	ds_write_b16_d16_hi v112, v68 offset:1088
	ds_write_b16 v112, v69 offset:1152
	ds_write_b16_d16_hi v112, v69 offset:1216
	ds_write_b16 v112, v70 offset:1536
	ds_write_b16_d16_hi v112, v70 offset:1600
	ds_write_b16 v112, v71 offset:1664
	ds_write_b16_d16_hi v112, v71 offset:1728
	ds_read_b128 v[96:99], v113
	ds_read_b128 v[100:103], v113 offset:1024
	v_cvt_pk_bf16_f32 v72, v0, v1
	v_cvt_pk_bf16_f32 v73, v2, v3
	v_cvt_pk_bf16_f32 v74, v4, v5
	v_cvt_pk_bf16_f32 v75, v6, v7
	v_cvt_pk_bf16_f32 v76, v8, v9
	v_cvt_pk_bf16_f32 v77, v10, v11
	v_cvt_pk_bf16_f32 v78, v12, v13
	v_cvt_pk_bf16_f32 v79, v14, v15
	ds_write_b16 v112, v72
	ds_write_b16_d16_hi v112, v72 offset:64
	ds_write_b16 v112, v73 offset:128
	ds_write_b16_d16_hi v112, v73 offset:192
	ds_write_b16 v112, v74 offset:512
	ds_write_b16_d16_hi v112, v74 offset:576
	ds_write_b16 v112, v75 offset:640
	ds_write_b16_d16_hi v112, v75 offset:704
	ds_write_b16 v112, v76 offset:1024
	ds_write_b16_d16_hi v112, v76 offset:1088
	ds_write_b16 v112, v77 offset:1152
	ds_write_b16_d16_hi v112, v77 offset:1216
	ds_write_b16 v112, v78 offset:1536
	ds_write_b16_d16_hi v112, v78 offset:1600
	ds_write_b16 v112, v79 offset:1664
	ds_write_b16_d16_hi v112, v79 offset:1728
	ds_read_b128 v[104:107], v113
	ds_read_b128 v[108:111], v113 offset:1024
	s_waitcnt lgkmcnt(0)
	global_store_dwordx4 v114, v[80:83], s[98:99]
	s_add_u32 s100, s98, 0x8000
	s_addc_u32 s101, s99, 0
	global_store_dwordx4 v114, v[84:87], s[100:101]
	global_store_dwordx4 v114, v[88:91], s[98:99] offset:64
	global_store_dwordx4 v114, v[92:95], s[100:101] offset:64
	s_add_u32 s98, s98, 0x10000
	s_addc_u32 s99, s99, 0
	global_store_dwordx4 v114, v[96:99], s[98:99]
	s_add_u32 s100, s98, 0x8000
	s_addc_u32 s101, s99, 0
	global_store_dwordx4 v114, v[100:103], s[100:101]
	global_store_dwordx4 v114, v[104:107], s[98:99] offset:64
	global_store_dwordx4 v114, v[108:111], s[100:101] offset:64
	s_branch .Lodin4_next
